# final RMSNorm: norm-weight pieces loaded once before the row loop; out-projection phase: the 24 slab loads of a merged context row requested together; otherwise as v87
# baseline (speedup 1.0000x reference)
; __global__ void __launch_bounds__(NTHR, 2) mk_fwd(Args args) {
;     ...
;             for (int r = gw; r < NB * SEQ; r += NGW) { const int b = r >> 13, s = r & 8191;
;                 const f32x4* xr = (const f32x4*)(X + (size_t)(b * TB + LC + s) * 1024) + lane; f32x4 v[4]; float ss = 0.f;
; #pragma unroll
;                 for (int j = 0; j < 4; ++j) { v[j] = xr[64 * j]; ss += (v[j][0] * v[j][0] + v[j][1] * v[j][1]) + (v[j][2] * v[j][2] + v[j][3] * v[j][3]); }
;                 const float rstd = rsqrtf(wave_sum(ss) * (1.f / 1024.f) + EPS);
; #pragma unroll
;                 for (int j = 0; j < 4; ++j) { const f32x4 w = ((const f32x4*)ap->in[I_FNORM])[64 * j + lane]; f32x4 o; o[0] = v[j][0] * rstd * w[0]; o[1] = v[j][1] * rstd * w[1]; o[2] = v[j][2] * rstd * w[2]; o[3] = v[j][3] * rstd * w[3];
;                     ((f32x4*)(ap->out + (size_t)r * 1024))[64 * j + lane] = o; } }
.LBB0_27:
	s_cmp_eq_u32 s90, 45
	s_mov_b64 s[2:3], -1
	s_cbranch_scc0 .LBB0_32
	v_readlane_b32 s2, v254, 21
	s_cmpk_gt_i32 s2, 0x3fff
	v_readlane_b32 s24, v254, 23
	v_readlane_b32 s3, v254, 22
	v_readlane_b32 s25, v254, 24
	s_cbranch_scc1 .LBB0_31
	v_readlane_b32 s2, v254, 25
	v_cmp_lt_i32_e32 vcc, v220, v219
	s_load_dwordx4 s[16:19], s[6:7], 0xc8
	v_lshlrev_b32_e32 v4, 4, v202
	v_mov_b32_e32 v5, v36
	v_readlane_b32 s3, v254, 26
	v_cndmask_b32_e32 v2, v218, v220, vcc
	v_cmp_lt_i32_e32 vcc, v221, v219
	v_lshl_add_u64 v[0:1], s[2:3], 0, v[4:5]
	v_lshlrev_b32_e32 v6, 2, v2
	v_cndmask_b32_e32 v2, v218, v221, vcc
	v_cmp_lt_i32_e32 vcc, v222, v219
	v_readlane_b32 s2, v254, 21
	v_lshlrev_b32_e32 v7, 2, v2
	v_cndmask_b32_e32 v2, v218, v222, vcc
	v_cmp_lt_i32_e32 vcc, v223, v219
	v_readlane_b32 s3, v254, 22
	s_mov_b32 s14, s2
	s_ashr_i32 s15, s2, 31
	v_lshlrev_b32_e32 v8, 2, v2
	v_cndmask_b32_e32 v2, v218, v223, vcc
	v_cmp_lt_i32_e32 vcc, v224, v219
	s_lshl_b64 s[2:3], s[14:15], 12
	v_lshlrev_b32_e32 v9, 2, v2
	v_cndmask_b32_e32 v2, v218, v224, vcc
	v_cmp_lt_i32_e32 vcc, v225, v219
	s_waitcnt lgkmcnt(0)
	s_add_u32 s2, s18, s2
	v_lshlrev_b32_e32 v10, 2, v2
	v_cndmask_b32_e32 v2, v218, v225, vcc
	s_addc_u32 s3, s19, s3
	s_mov_b32 s10, s14
	v_lshlrev_b32_e32 v11, 2, v2
	v_lshl_add_u64 v[2:3], s[16:17], 0, v[4:5]
	v_lshl_add_u64 v[4:5], s[2:3], 0, v[4:5]
	s_mov_b64 s[2:3], 0xc00
	s_ashr_i32 s25, s24, 31
	v_writelane_b32 v254, s10, 21
	v_lshl_add_u64 v[4:5], v[4:5], 0, s[2:3]
	s_lshl_b64 s[2:3], s[24:25], 12
	v_writelane_b32 v254, s11, 22
	s_mov_b32 s10, s14
	global_load_dwordx4 v[60:63], v[2:3], off
	global_load_dwordx4 v[64:67], v[2:3], off offset:1024
	global_load_dwordx4 v[68:71], v[2:3], off offset:2048
	global_load_dwordx4 v[72:75], v[2:3], off offset:3072
	s_waitcnt vmcnt(0)
.LBB0_30:
	s_ashr_i32 s11, s10, 13
	s_and_b32 s13, s10, 0x1fff
	s_mulk_i32 s11, 0x2100
	s_add_i32 s11, s13, s11
	s_add_i32 s14, s11, 0x100
	s_ashr_i32 s15, s14, 31
	s_lshl_b64 s[14:15], s[14:15], 12
	v_lshl_add_u64 v[24:25], v[0:1], 0, s[14:15]
	global_load_dwordx4 v[12:15], v[24:25], off
	global_load_dwordx4 v[16:19], v[24:25], off offset:1024
	global_load_dwordx4 v[20:23], v[24:25], off offset:2048
	s_nop 0
	global_load_dwordx4 v[24:27], v[24:25], off offset:3072
	s_nop 0
	s_add_i32 s10, s10, s24
	s_cmpk_gt_i32 s10, 0x3fff
	s_waitcnt vmcnt(0)
	v_pk_mul_f32 v[32:33], v[14:15], v[14:15]
	v_pk_mul_f32 v[34:35], v[12:13], v[12:13]
	s_waitcnt vmcnt(2)
	v_pk_mul_f32 v[38:39], v[18:19], v[18:19]
	v_pk_mul_f32 v[42:43], v[16:17], v[16:17]
	v_pk_mov_b32 v[52:53], v[34:35], v[32:33] op_sel:[1,0]
	v_mov_b32_e32 v35, v33
	v_pk_mov_b32 v[32:33], v[42:43], v[38:39] op_sel:[1,0]
	v_mov_b32_e32 v43, v39
	s_waitcnt vmcnt(0)
	v_mul_f32_e32 v51, v26, v26
	v_mul_f32_e32 v48, v21, v21
	v_mul_f32_e32 v50, v23, v23
	v_pk_add_f32 v[34:35], v[52:53], v[34:35]
	v_pk_add_f32 v[32:33], v[32:33], v[42:43]
	v_mul_f32_e32 v37, v24, v24
	v_mul_f32_e32 v41, v25, v25
	v_mul_f32_e32 v54, v27, v27
	v_pk_fma_f32 v[38:39], v[20:21], v[20:21], v[48:49] op_sel_hi:[1,1,0]
	v_pk_fma_f32 v[48:49], v[22:23], v[22:23], v[50:51] op_sel_hi:[1,1,0]
	v_pk_add_f32 v[34:35], v[34:35], v[34:35] op_sel:[0,1] op_sel_hi:[1,0]
	v_pk_add_f32 v[32:33], v[32:33], v[32:33] op_sel:[0,1] op_sel_hi:[1,0]
	v_mov_b32_e32 v39, v51
	v_mov_b32_e32 v49, v54
	v_mov_b32_e32 v35, v37
	v_mov_b32_e32 v33, v41
	v_pk_add_f32 v[38:39], v[38:39], v[48:49]
	v_pk_add_f32 v[32:33], v[34:35], v[32:33]
	s_nop 0
	v_pk_add_f32 v[32:33], v[32:33], v[38:39]
	s_nop 0
	v_add_f32_e32 v32, v32, v33
	ds_bpermute_b32 v33, v6, v32
	s_waitcnt lgkmcnt(0)
	v_add_f32_e32 v32, v32, v33
	ds_bpermute_b32 v33, v7, v32
	s_waitcnt lgkmcnt(0)
	v_add_f32_e32 v32, v32, v33
	ds_bpermute_b32 v33, v8, v32
	s_waitcnt lgkmcnt(0)
	v_add_f32_e32 v32, v32, v33
	ds_bpermute_b32 v33, v9, v32
	s_waitcnt lgkmcnt(0)
	v_add_f32_e32 v32, v32, v33
	ds_bpermute_b32 v33, v10, v32
	s_waitcnt lgkmcnt(0)
	v_add_f32_e32 v32, v32, v33
	ds_bpermute_b32 v33, v11, v32
	s_waitcnt lgkmcnt(0)
	v_add_f32_e32 v32, v32, v33
	v_fmamk_f32 v32, v32, 0x3a800000, v216
	v_mul_f32_e32 v33, 0x4b800000, v32
	v_cmp_gt_f32_e32 vcc, s33, v32
	s_nop 1
	v_cndmask_b32_e32 v32, v32, v33, vcc
	v_rsq_f32_e32 v32, v32
	s_nop 0
	v_mul_f32_e32 v33, 0x45800000, v32
	v_cndmask_b32_e32 v32, v32, v33, vcc
	v_pk_mul_f32 v[12:13], v[32:33], v[12:13] op_sel_hi:[0,1]
	v_pk_mul_f32 v[14:15], v[32:33], v[14:15] op_sel_hi:[0,1]
	v_pk_mul_f32 v[14:15], v[62:63], v[14:15]
	v_pk_mul_f32 v[12:13], v[60:61], v[12:13]
	global_store_dwordx4 v[4:5], v[12:15], off offset:-3072
	v_pk_mul_f32 v[18:19], v[32:33], v[18:19] op_sel_hi:[0,1]
	v_pk_mul_f32 v[16:17], v[32:33], v[16:17] op_sel_hi:[0,1]
	v_pk_mul_f32 v[12:13], v[64:65], v[16:17]
	v_pk_mul_f32 v[14:15], v[66:67], v[18:19]
	global_store_dwordx4 v[4:5], v[12:15], off offset:-2048
	v_pk_mul_f32 v[16:17], v[32:33], v[22:23] op_sel_hi:[0,1]
	v_pk_mul_f32 v[18:19], v[32:33], v[20:21] op_sel_hi:[0,1]
	v_pk_mul_f32 v[12:13], v[68:69], v[18:19]
	v_pk_mul_f32 v[14:15], v[70:71], v[16:17]
	global_store_dwordx4 v[4:5], v[12:15], off offset:-1024
	v_pk_mul_f32 v[16:17], v[32:33], v[26:27] op_sel_hi:[0,1]
	v_pk_mul_f32 v[18:19], v[32:33], v[24:25] op_sel_hi:[0,1]
	v_pk_mul_f32 v[12:13], v[72:73], v[18:19]
	v_pk_mul_f32 v[14:15], v[74:75], v[16:17]
	global_store_dwordx4 v[4:5], v[12:15], off
	v_lshl_add_u64 v[4:5], v[4:5], 0, s[2:3]
	s_cbranch_scc0 .LBB0_30

; __device__ __forceinline__ unsigned pk2(float lo, float hi) { f32x2_t v = {lo, hi}; bf16x2_t b = __builtin_convertvector(v, bf16x2_t); return __builtin_bit_cast(unsigned, b); }
; __global__ void __launch_bounds__(NTHR, 2) mk_fwd(Args args) {
;     ...
;                 for (int r = gw; r < 512; r += NGW) { const int t = (r < 256) ? r : (TB + r - 256);
;                     const f32x4* sp = (const f32x4*)((const float*)(ws + O_CQ) + (size_t)r * 1024);
; #pragma unroll
;                     for (int j = 0; j < 4; ++j) { f32x4 a = sp[64 * j + lane];
; #pragma unroll
;                         for (int q = 1; q < 6; ++q) a = a + sp[(size_t)q * 512 * 256 + 64 * j + lane];
;                         u32x2 o; o.x = pk2(a[0], a[1]); o.y = pk2(a[2], a[3]); ((u32x2*)(HM + (size_t)t * 1024))[64 * j + lane] = o; } }
.LBB0_158:
	v_add_co_u32_e32 v28, vcc, 0x200000, v2
	global_load_dwordx4 v[4:7], v[2:3], off
	s_nop 0
	v_addc_co_u32_e32 v29, vcc, 0, v3, vcc
	v_add_co_u32_e32 v30, vcc, 0x400000, v2
	s_add_i32 s3, s2, 0x2000
	s_nop 0
	v_addc_co_u32_e32 v31, vcc, 0, v3, vcc
	v_add_co_u32_e32 v32, vcc, 0x600000, v2
	global_load_dwordx4 v[8:11], v[28:29], off
	global_load_dwordx4 v[12:15], v[30:31], off
	v_addc_co_u32_e32 v33, vcc, 0, v3, vcc
	v_add_co_u32_e32 v34, vcc, s33, v2
	s_cmpk_lt_i32 s2, 0x100
	s_nop 0
	v_addc_co_u32_e32 v35, vcc, 0, v3, vcc
	v_add_co_u32_e32 v38, vcc, s13, v2
	global_load_dwordx4 v[16:19], v[32:33], off
	global_load_dwordx4 v[20:23], v[34:35], off
	v_addc_co_u32_e32 v39, vcc, 0, v3, vcc
	global_load_dwordx4 v[24:27], v[38:39], off
	s_cselect_b32 s10, s2, s3
	s_ashr_i32 s11, s10, 31
	s_lshl_b64 s[10:11], s[10:11], 11
	v_lshl_add_u64 v[42:43], v[0:1], 0, s[10:11]
	s_add_i32 s2, s2, s24
	s_cmpk_gt_i32 s2, 0x1ff
	global_load_dwordx4 v[60:63], v[2:3], off offset:1024
	global_load_dwordx4 v[64:67], v[28:29], off offset:1024
	global_load_dwordx4 v[68:71], v[30:31], off offset:1024
	global_load_dwordx4 v[72:75], v[32:33], off offset:1024
	global_load_dwordx4 v[76:79], v[34:35], off offset:1024
	global_load_dwordx4 v[80:83], v[38:39], off offset:1024
	global_load_dwordx4 v[84:87], v[2:3], off offset:2048
	global_load_dwordx4 v[88:91], v[28:29], off offset:2048
	global_load_dwordx4 v[92:95], v[30:31], off offset:2048
	global_load_dwordx4 v[96:99], v[32:33], off offset:2048
	global_load_dwordx4 v[100:103], v[34:35], off offset:2048
	global_load_dwordx4 v[104:107], v[38:39], off offset:2048
	global_load_dwordx4 v[108:111], v[2:3], off offset:3072
	global_load_dwordx4 v[112:115], v[28:29], off offset:3072
	global_load_dwordx4 v[116:119], v[30:31], off offset:3072
	global_load_dwordx4 v[120:123], v[32:33], off offset:3072
	global_load_dwordx4 v[124:127], v[34:35], off offset:3072
	global_load_dwordx4 v[128:131], v[38:39], off offset:3072
	s_waitcnt vmcnt(18)
	v_pk_add_f32 v[6:7], v[6:7], v[10:11]
	v_pk_add_f32 v[4:5], v[4:5], v[8:9]
	v_pk_add_f32 v[6:7], v[6:7], v[14:15]
	v_pk_add_f32 v[4:5], v[4:5], v[12:13]
	v_pk_add_f32 v[6:7], v[6:7], v[18:19]
	v_pk_add_f32 v[4:5], v[4:5], v[16:17]
	v_pk_add_f32 v[6:7], v[6:7], v[22:23]
	v_pk_add_f32 v[4:5], v[4:5], v[20:21]
	v_pk_add_f32 v[6:7], v[6:7], v[26:27]
	v_pk_add_f32 v[4:5], v[4:5], v[24:25]
	s_nop 0
	v_cvt_pk_bf16_f32 v4, v4, v5
	v_cvt_pk_bf16_f32 v5, v6, v7
	global_store_dwordx2 v[42:43], v[4:5], off
	s_waitcnt vmcnt(13)
	v_pk_add_f32 v[62:63], v[62:63], v[66:67]
	v_pk_add_f32 v[60:61], v[60:61], v[64:65]
	v_pk_add_f32 v[62:63], v[62:63], v[70:71]
	v_pk_add_f32 v[60:61], v[60:61], v[68:69]
	v_pk_add_f32 v[62:63], v[62:63], v[74:75]
	v_pk_add_f32 v[60:61], v[60:61], v[72:73]
	v_pk_add_f32 v[62:63], v[62:63], v[78:79]
	v_pk_add_f32 v[60:61], v[60:61], v[76:77]
	v_pk_add_f32 v[62:63], v[62:63], v[82:83]
	v_pk_add_f32 v[60:61], v[60:61], v[80:81]
	s_nop 0
	v_cvt_pk_bf16_f32 v60, v60, v61
	v_cvt_pk_bf16_f32 v61, v62, v63
	global_store_dwordx2 v[42:43], v[60:61], off offset:512
	s_waitcnt vmcnt(8)
	v_pk_add_f32 v[86:87], v[86:87], v[90:91]
	v_pk_add_f32 v[84:85], v[84:85], v[88:89]
	v_pk_add_f32 v[86:87], v[86:87], v[94:95]
	v_pk_add_f32 v[84:85], v[84:85], v[92:93]
	v_pk_add_f32 v[86:87], v[86:87], v[98:99]
	v_pk_add_f32 v[84:85], v[84:85], v[96:97]
	v_pk_add_f32 v[86:87], v[86:87], v[102:103]
	v_pk_add_f32 v[84:85], v[84:85], v[100:101]
	v_pk_add_f32 v[86:87], v[86:87], v[106:107]
	v_pk_add_f32 v[84:85], v[84:85], v[104:105]
	s_nop 0
	v_cvt_pk_bf16_f32 v84, v84, v85
	v_cvt_pk_bf16_f32 v85, v86, v87
	global_store_dwordx2 v[42:43], v[84:85], off offset:1024
	s_waitcnt vmcnt(3)
	v_lshl_add_u64 v[2:3], v[2:3], 0, s[0:1]
	v_pk_add_f32 v[110:111], v[110:111], v[114:115]
	v_pk_add_f32 v[108:109], v[108:109], v[112:113]
	v_pk_add_f32 v[110:111], v[110:111], v[118:119]
	v_pk_add_f32 v[108:109], v[108:109], v[116:117]
	v_pk_add_f32 v[110:111], v[110:111], v[122:123]
	v_pk_add_f32 v[108:109], v[108:109], v[120:121]
	v_pk_add_f32 v[110:111], v[110:111], v[126:127]
	v_pk_add_f32 v[108:109], v[108:109], v[124:125]
	v_pk_add_f32 v[110:111], v[110:111], v[130:131]
	v_pk_add_f32 v[108:109], v[108:109], v[128:129]
	s_nop 0
	v_cvt_pk_bf16_f32 v108, v108, v109
	v_cvt_pk_bf16_f32 v109, v110, v111
	global_store_dwordx2 v[42:43], v[108:109], off offset:1536
	s_cbranch_scc0 .LBB0_158
